# NA attention phase: blocks >= 256 run their 3 units in reverse order (dense ctx unit first) so co-resident blocks are in different unit kinds
# speedup vs baseline: 1.0168x; 1.0014x over previous
.LBB0_1754:
	s_cmp_gt_i32 s22, 14
	s_cselect_b64 s[4:5], -1, 0
	s_cmp_lt_i32 s23, 15
	s_cselect_b64 s[6:7], -1, 0
	s_or_b64 s[4:5], s[4:5], s[6:7]
	s_and_b64 vcc, exec, s[4:5]
	s_cbranch_vccnz .LBB0_1856
	s_cmpk_gt_i32 s2, 0x5ff
	v_and_b32_e32 v73, 0x3ff, v0
	s_cbranch_scc1 .LBB0_1803
	s_waitcnt vmcnt(0)
	v_lshrrev_b32_e32 v6, 5, v73
	v_bfe_u32 v105, v73, 1, 3
	v_bfe_u32 v103, v73, 5, 1
	v_bitop3_b32 v6, v6, v105, 1 bitop3:0x6c
	v_lshlrev_b32_e32 v107, 4, v6
	v_bitop3_b32 v6, v103, v105, 2 bitop3:0x36
	v_lshlrev_b32_e32 v109, 4, v6
	v_bitop3_b32 v6, v103, v105, 4 bitop3:0x36
	v_lshlrev_b32_e32 v111, 4, v6
	v_bitop3_b32 v6, v103, v105, 6 bitop3:0x36
	v_lshlrev_b32_e32 v8, 7, v73
	v_lshlrev_b32_e32 v113, 4, v6
	v_lshrrev_b32_e32 v6, 6, v73
	v_and_b32_e32 v106, 0xf80, v8
	v_lshlrev_b32_e32 v8, 4, v6
	v_lshlrev_b32_e32 v4, 4, v73
	v_and_or_b32 v9, v73, 15, v8
	v_sub_u32_e64 v8, v8, 8 clamp
	v_and_b32_e32 v104, 0x3c00, v4
	v_lshlrev_b32_e32 v4, 3, v103
	v_sub_u32_e64 v10, v9, 8 clamp
	v_min_u32_e32 v116, 32, v8
	v_min_u32_e32 v8, 48, v10
	v_add_u32_e32 v13, v116, v4
	v_add_u32_e32 v12, 16, v8
	v_or_b32_e32 v14, 1, v13
	v_cmp_ge_u32_e32 vcc, v14, v8
	v_cmp_ge_u32_e64 s[4:5], v13, v8
	v_cmp_lt_u32_e64 s[8:9], v14, v12
	v_cmp_lt_u32_e64 s[10:11], v13, v12
	v_mov_b32_e32 v14, 0xf149f2ca
	s_and_b64 s[8:9], vcc, s[8:9]
	s_and_b64 s[4:5], s[4:5], s[10:11]
	v_or_b32_e32 v15, 3, v13
	v_or_b32_e32 v16, 2, v13
	v_cndmask_b32_e64 v77, v14, 0, s[8:9]
	v_cndmask_b32_e64 v76, v14, 0, s[4:5]
	v_cmp_ge_u32_e32 vcc, v15, v8
	v_cmp_ge_u32_e64 s[4:5], v16, v8
	v_cmp_lt_u32_e64 s[8:9], v15, v12
	v_cmp_lt_u32_e64 s[10:11], v16, v12
	s_and_b64 s[8:9], vcc, s[8:9]
	s_and_b64 s[4:5], s[4:5], s[10:11]
	v_or_b32_e32 v15, 5, v13
	v_or_b32_e32 v16, 4, v13
	v_cndmask_b32_e64 v79, v14, 0, s[8:9]
	v_cndmask_b32_e64 v78, v14, 0, s[4:5]
	v_cmp_ge_u32_e32 vcc, v15, v8
	v_cmp_ge_u32_e64 s[4:5], v16, v8
	v_cmp_lt_u32_e64 s[8:9], v15, v12
	v_cmp_lt_u32_e64 s[10:11], v16, v12
	s_and_b64 s[8:9], vcc, s[8:9]
	s_and_b64 s[4:5], s[4:5], s[10:11]
	v_or_b32_e32 v15, 7, v13
	v_or_b32_e32 v16, 6, v13
	v_cndmask_b32_e64 v81, v14, 0, s[8:9]
	v_cndmask_b32_e64 v80, v14, 0, s[4:5]
	v_cmp_ge_u32_e32 vcc, v15, v8
	v_cmp_ge_u32_e64 s[4:5], v16, v8
	v_cmp_lt_u32_e64 s[8:9], v15, v12
	v_cmp_lt_u32_e64 s[10:11], v16, v12
	s_and_b64 s[8:9], vcc, s[8:9]
	s_and_b64 s[4:5], s[4:5], s[10:11]
	v_add_u32_e32 v15, 16, v13
	v_add_u32_e32 v16, 17, v13
	v_cndmask_b32_e64 v83, v14, 0, s[8:9]
	v_cndmask_b32_e64 v82, v14, 0, s[4:5]
	v_cmp_ge_u32_e32 vcc, v16, v8
	v_cmp_ge_u32_e64 s[4:5], v15, v8
	v_cmp_lt_u32_e64 s[8:9], v16, v12
	v_cmp_lt_u32_e64 s[10:11], v13, v8
	s_and_b64 s[8:9], vcc, s[8:9]
	s_and_b64 s[4:5], s[4:5], s[10:11]
	v_add_u32_e32 v15, 18, v13
	v_add_u32_e32 v16, 19, v13
	v_cndmask_b32_e64 v85, v14, 0, s[8:9]
	v_cndmask_b32_e64 v84, v14, 0, s[4:5]
	v_cmp_ge_u32_e32 vcc, v16, v8
	v_cmp_ge_u32_e64 s[4:5], v15, v8
	v_cmp_lt_u32_e64 s[8:9], v16, v12
	v_cmp_lt_u32_e64 s[10:11], v15, v12
	v_lshrrev_b32_e32 v7, 3, v73
	s_and_b64 s[8:9], vcc, s[8:9]
	s_and_b64 s[4:5], s[4:5], s[10:11]
	v_add_u32_e32 v15, 20, v13
	v_add_u32_e32 v16, 21, v13
	v_lshlrev_b32_e32 v66, 11, v7
	v_lshlrev_b32_e32 v70, 9, v7
	v_mul_hi_u32_u24_e32 v75, 0x1200, v7
	v_mul_u32_u24_e32 v74, 0x1200, v7
	v_and_b32_e32 v7, 63, v73
	v_cndmask_b32_e64 v87, v14, 0, s[8:9]
	v_cndmask_b32_e64 v86, v14, 0, s[4:5]
	v_cmp_ge_u32_e32 vcc, v16, v8
	v_cmp_ge_u32_e64 s[4:5], v15, v8
	v_cmp_lt_u32_e64 s[8:9], v16, v12
	v_cmp_lt_u32_e64 s[10:11], v15, v12
	v_and_b32_e32 v3, 31, v73
	v_lshrrev_b32_e32 v5, 1, v73
	s_waitcnt lgkmcnt(0)
	s_movk_i32 s3, 0x1e0
	v_lshlrev_b32_e32 v10, 1, v73
	v_add_u32_e32 v7, -16, v7
	s_and_b64 s[8:9], vcc, s[8:9]
	s_and_b64 s[4:5], s[4:5], s[10:11]
	v_add_u32_e32 v15, 22, v13
	v_add_u32_e32 v13, 23, v13
	v_and_or_b32 v102, v5, s3, v3
	v_lshrrev_b32_e32 v2, 4, v73
	v_and_b32_e32 v5, 4, v5
	v_and_b32_e32 v10, 8, v10
	v_med3_i32 v11, v7, 0, 30
	v_cmp_gt_u32_e64 s[6:7], 31, v7
	v_and_b32_e32 v7, 19, v73
	v_cndmask_b32_e64 v89, v14, 0, s[8:9]
	v_cndmask_b32_e64 v88, v14, 0, s[4:5]
	v_cmp_ge_u32_e32 vcc, v13, v8
	v_cmp_ge_u32_e64 s[4:5], v15, v8
	v_cmp_lt_u32_e64 s[8:9], v13, v12
	v_cmp_lt_u32_e64 s[10:11], v15, v12
	v_xor_b32_e32 v2, v2, v73
	s_and_b64 s[8:9], vcc, s[8:9]
	s_and_b64 s[4:5], s[4:5], s[10:11]
	v_or3_b32 v118, v5, v7, v10
	v_or_b32_e32 v5, 16, v4
	s_load_dwordx8 s[12:19], s[0:1], 0x160
	s_load_dwordx2 s[26:27], s[0:1], 0x78
	s_load_dwordx2 s[28:29], s[0:1], 0x98
	v_lshlrev_b32_e32 v2, 3, v2
	v_sub_u32_e32 v5, v5, v9
	s_add_u32 s10, s0, 0x468
	v_mbcnt_lo_u32_b32 v132, -1, 0
	v_and_b32_e32 v2, 56, v2
	v_cndmask_b32_e64 v90, v14, 0, s[4:5]
	v_lshlrev_b32_e32 v7, 2, v116
	v_lshlrev_b32_e32 v119, 7, v3
	s_addc_u32 s11, s1, 0
	v_lshlrev_b32_e32 v3, 2, v5
	s_mov_b32 s4, 0x10000
	v_mbcnt_hi_u32_b32 v133, -1, v132
	v_mov_b32_e32 v69, 0
	s_waitcnt lgkmcnt(0)
	s_add_u32 s3, s16, 0x800000
	v_add3_u32 v120, v3, v7, s4
	v_mov_b32_e32 v3, 0x10000
	v_lshlrev_b32_e32 v68, 1, v2
	v_and_b32_e32 v2, 64, v133
	v_mov_b32_e32 v67, v69
	v_mov_b32_e32 v71, v69
	v_or_b32_e32 v108, 2, v103
	v_or_b32_e32 v110, 4, v103
	v_or_b32_e32 v112, 6, v103
	v_lshlrev_b32_e32 v72, 2, v103
	v_bfe_u32 v114, v73, 4, 1
	v_or_b32_e32 v115, 0x1000, v9
	v_lshlrev_b32_e32 v117, 10, v6
	s_mov_b32 s25, 0
	v_cndmask_b32_e64 v91, v14, 0, s[8:9]
	s_mov_b64 s[30:31], 0x800000
	s_addc_u32 s84, s17, 0
	v_add_u32_e32 v121, 0xffffff00, v73
	v_lshl_or_b32 v122, v73, 2, v3
	v_mad_u32_u24 v123, v6, 31, v11
	v_add_u32_e32 v124, -15, v6
	s_mov_b64 s[34:35], 0x10000
	v_add_u32_e32 v125, 0x1000, v104
	v_add_u32_e32 v126, 0x2000, v104
	s_mov_b64 s[36:37], 0x4000
	v_add_u32_e32 v127, 0x3000, v104
	s_mov_b64 s[38:39], 0x20000
	v_or_b32_e32 v128, 0x4000, v104
	s_mov_b64 s[40:41], 0x30000
	v_add_u32_e32 v129, 0x5000, v104
	s_mov_b64 s[42:43], 0x80
	v_add_u32_e32 v130, 0x6000, v104
	s_mov_b64 s[44:45], 0x4080
	v_add_u32_e32 v131, 0x7000, v104
	s_mov_b64 s[46:47], 0x40000
	s_mov_b64 s[48:49], 0x50000
	s_mov_b64 s[50:51], 0x100
	s_mov_b64 s[52:53], 0x4100
	s_mov_b64 s[54:55], 0x60000
	s_mov_b64 s[56:57], 0x70000
	s_mov_b64 s[58:59], 0x180
	s_mov_b64 s[60:61], 0x4180
	s_mov_b64 s[62:63], 0x1f0
	s_movk_i32 s85, 0x2ff
	s_mov_b64 s[64:65], 0x24000
	s_mov_b64 s[66:67], 0x810000
	s_mov_b64 s[68:69], 0x820000
	s_mov_b64 s[70:71], 0x830000
	s_mov_b64 s[72:73], 0x24080
	s_mov_b64 s[74:75], 0x840000
	s_mov_b64 s[76:77], 0x850000
	s_mov_b64 s[78:79], 0x24100
	v_lshlrev_b32_e32 v92, 1, v4
	v_xor_b32_e32 v134, 32, v133
	v_add_u32_e32 v135, 64, v2
	v_mov_b32_e32 v136, 0x3c0
	s_mov_b32 s86, s2
	s_load_dword s96, s[0:1], 0x468
	s_waitcnt lgkmcnt(0)
	s_cmpk_lg_u32 s96, 0x200
	s_cbranch_scc1 .Lna14_order_done
	s_cmpk_lt_u32 s2, 0x100
	s_cbranch_scc1 .Lna14_order_done
	s_add_i32 s86, s2, 0x400
	s_movk_i32 s96, 0xfe00
.Lna14_order_done:
	s_branch .LBB0_1760

.LBB0_1759:
	v_cvt_pk_bf16_f32 v2, v2, v3
	v_and_b32_e32 v3, 0xffff0000, v37
	v_mul_f32_e32 v3, v5, v3
	v_cvt_pk_bf16_f32 v3, v4, v3
	v_lshlrev_b32_e32 v4, 1, v72
	v_mov_b32_e32 v5, v69
	v_lshl_add_u64 v[4:5], v[34:35], 0, v[4:5]
	global_store_dwordx2 v[4:5], v[2:3], off offset:112
	s_mov_b32 s4, s96
	s_waitcnt lgkmcnt(0)
	s_add_i32 s86, s4, s86
	s_cmpk_lt_u32 s86, 0x600
	s_cbranch_scc0 .LBB0_1803
